# combo3 + GEMM2 epilogue: x loads batched/rolling with counted waits, row-sum reductions and atomics batched
# speedup vs baseline: 1.0440x; 1.0111x over previous
; #define PG8_STAGE(bufoff, gbase, voff) do { _Pragma("unroll") for (int _i = 0; _i < 2; ++_i) \
;         __builtin_amdgcn_global_load_lds((const unsigned*)((const char*)(gbase) + (voff)[_i]), (LAS unsigned*)(lds + (bufoff) + ldsw + _i * 8192), 16, 0, 0); } while (0)
; #define PG8_LDA(dst, b, h) do { _Pragma("unroll") for (int m = 0; m < 4; ++m) _Pragma("unroll") for (int k = 0; k < 2; ++k) dst[m][k] = *(const LAS bf16x8*)(lds + PG8_SA(b, h) + aoff + m * 2048 + k * 1024); } while (0)
; #define PG8_LDB(dst, b, h) do { _Pragma("unroll") for (int n = 0; n < 2; ++n) _Pragma("unroll") for (int k = 0; k < 2; ++k) dst[n][k] = *(const LAS bf16x8*)(lds + PG8_SB(b, h) + boff + n * 2048 + k * 1024); } while (0)
; #define PG8_MMA(ai, bj, At, Bt) do { __builtin_amdgcn_s_setprio(1); _Pragma("unroll") for (int m = 0; m < 4; ++m) _Pragma("unroll") for (int n = 0; n < 2; ++n) _Pragma("unroll") for (int k = 0; k < 2; ++k) \
;         acc[ai][bj][m][n] = __builtin_amdgcn_mfma_f32_16x16x32_bf16(Bt[n][k], At[m][k], acc[ai][bj][m][n], 0, 0, 0); __builtin_amdgcn_s_setprio(0); } while (0)
; #define PG8_WAIT_L(n) asm volatile("s_waitcnt lgkmcnt(" #n ")" ::: "memory")
; #define PG8_BAR __builtin_amdgcn_s_barrier()
; #define PG8_SCHED __builtin_amdgcn_sched_barrier(0)
; template <class Epi>
; __device__ __forceinline__ void gemm_phase(LAS unsigned char* lds, const Gemm g, const StaticOrder& S, const Epi& E) {
;     ...
;             PG8_LDB(B0, 0, 0); PG8_SCHED; PG8_LDA(At, 0, 0); PG8_STAGE(PG8_SA(1, 1), a1 + hstepA, voffA);
;             PG8_WAIT_L(8); PG8_BAR; PG8_WAIT_L(0); PG8_MMA(0, 0, At, B0); PG8_BAR; PG8_SCHED;
;             PG8_LDB(B1, 0, 1); PG8_STAGE(PG8_SB(0, 0), b2, voffB);
;             PG8_BAR; PG8_WAIT_L(0); PG8_MMA(0, 1, At, B1); PG8_BAR;
;             PG8_LDA(At, 0, 1); PG8_STAGE(PG8_SA(0, 0), a2, voffA);
;             PG8_BAR; PG8_WAIT_L(0); PG8_MMA(1, 0, At, B0); PG8_BAR; PG8_SCHED;
.LBB0_752:
	ds_read_b128 v[140:143], v150
	ds_read_b128 v[158:161], v150 offset:1024
	ds_read_b128 v[162:165], v150 offset:2048
	ds_read_b128 v[166:169], v150 offset:3072
	s_add_u32 s58, s56, 0xfffc0080
	s_addc_u32 s59, s57, -1
	s_cmp_eq_u32 s76, 12
	s_cselect_b32 s61, s0, s59
	s_cselect_b32 s60, s1, s58
	s_cselect_b32 s59, s29, s75
	s_cselect_b32 s58, s37, s43
	v_lshl_add_u64 v[144:145], s[56:57], 0, v[132:133]
	s_add_i32 m0, s34, 0xc000
	ds_read_b128 v[170:173], v151
	ds_read_b128 v[174:177], v151 offset:1024
	ds_read_b128 v[178:181], v151 offset:2048
	ds_read_b128 v[186:189], v151 offset:3072
	ds_read_b128 v[190:193], v151 offset:4096
	ds_read_b128 v[194:197], v151 offset:5120
	ds_read_b128 v[198:201], v151 offset:6144
	ds_read_b128 v[202:205], v151 offset:7168
	global_load_lds_dwordx4 v[144:145], off
	v_lshl_add_u64 v[144:145], s[56:57], 0, v[134:135]
	s_add_i32 m0, s34, 0xe000
	s_nop 0
	global_load_lds_dwordx4 v[144:145], off
	s_waitcnt lgkmcnt(8)
	s_barrier
	s_waitcnt lgkmcnt(0)
	s_setprio 1
	s_waitcnt lgkmcnt(0)
	v_mfma_f32_16x16x32_bf16 v[124:127], v[140:143], v[170:173], v[124:127]
	v_mfma_f32_16x16x32_bf16 v[120:123], v[162:165], v[170:173], v[120:123]
	v_mfma_f32_16x16x32_bf16 v[108:111], v[140:143], v[178:181], v[108:111]
	v_mfma_f32_16x16x32_bf16 v[104:107], v[162:165], v[178:181], v[104:107]
	v_mfma_f32_16x16x32_bf16 v[92:95], v[140:143], v[190:193], v[92:95]
	v_mfma_f32_16x16x32_bf16 v[88:91], v[162:165], v[190:193], v[88:91]
	v_mfma_f32_16x16x32_bf16 v[76:79], v[140:143], v[198:201], v[76:79]
	v_mfma_f32_16x16x32_bf16 v[72:75], v[162:165], v[198:201], v[72:75]
	v_mfma_f32_16x16x32_bf16 v[124:127], v[158:161], v[174:177], v[124:127]
	v_mfma_f32_16x16x32_bf16 v[120:123], v[166:169], v[174:177], v[120:123]
	v_mfma_f32_16x16x32_bf16 v[108:111], v[158:161], v[186:189], v[108:111]
	v_mfma_f32_16x16x32_bf16 v[104:107], v[166:169], v[186:189], v[104:107]
	v_mfma_f32_16x16x32_bf16 v[92:95], v[158:161], v[194:197], v[92:95]
	v_mfma_f32_16x16x32_bf16 v[88:91], v[166:169], v[194:197], v[88:91]
	v_mfma_f32_16x16x32_bf16 v[76:79], v[158:161], v[202:205], v[76:79]
	v_mfma_f32_16x16x32_bf16 v[72:75], v[166:169], v[202:205], v[72:75]
	s_setprio 0
	s_barrier
	s_add_i32 s77, s73, s31
	v_lshl_add_u64 v[144:145], s[58:59], 0, v[128:129]
	s_mov_b32 m0, s77
	ds_read_b128 v[206:209], v152
	ds_read_b128 v[210:213], v152 offset:1024
	ds_read_b128 v[214:217], v152 offset:2048
	ds_read_b128 v[218:221], v152 offset:3072
	global_load_lds_dwordx4 v[144:145], off
	v_lshl_add_u64 v[154:155], s[58:59], 0, v[130:131]
	s_add_i32 m0, s77, 0x2000
	s_nop 0
	global_load_lds_dwordx4 v[154:155], off
	s_barrier
	s_waitcnt lgkmcnt(0)
	s_setprio 1
	s_waitcnt lgkmcnt(0)
	v_mfma_f32_16x16x32_bf16 v[116:119], v[206:209], v[170:173], v[116:119]
	v_mfma_f32_16x16x32_bf16 v[112:115], v[214:217], v[170:173], v[112:115]
	v_mfma_f32_16x16x32_bf16 v[100:103], v[206:209], v[178:181], v[100:103]
	v_mfma_f32_16x16x32_bf16 v[96:99], v[214:217], v[178:181], v[96:99]
	v_mfma_f32_16x16x32_bf16 v[84:87], v[206:209], v[190:193], v[84:87]
	v_mfma_f32_16x16x32_bf16 v[80:83], v[214:217], v[190:193], v[80:83]
	v_mfma_f32_16x16x32_bf16 v[68:71], v[206:209], v[198:201], v[68:71]
	v_mfma_f32_16x16x32_bf16 v[64:67], v[214:217], v[198:201], v[64:67]
	v_mfma_f32_16x16x32_bf16 v[116:119], v[210:213], v[174:177], v[116:119]
	v_mfma_f32_16x16x32_bf16 v[112:115], v[218:221], v[174:177], v[112:115]
	v_mfma_f32_16x16x32_bf16 v[100:103], v[210:213], v[186:189], v[100:103]
	v_mfma_f32_16x16x32_bf16 v[96:99], v[218:221], v[186:189], v[96:99]
	v_mfma_f32_16x16x32_bf16 v[84:87], v[210:213], v[194:197], v[84:87]
	v_mfma_f32_16x16x32_bf16 v[80:83], v[218:221], v[194:197], v[80:83]
	v_mfma_f32_16x16x32_bf16 v[68:71], v[210:213], v[202:205], v[68:71]
	v_mfma_f32_16x16x32_bf16 v[64:67], v[218:221], v[202:205], v[64:67]
	s_setprio 0
	s_mov_b32 m0, s34
	v_lshl_add_u64 v[182:183], s[60:61], 0, v[128:129]
	s_barrier
	ds_read_b128 v[170:173], v151 offset:16384
	ds_read_b128 v[174:177], v151 offset:17408
	ds_read_b128 v[178:181], v151 offset:18432
	ds_read_b128 v[186:189], v151 offset:19456
	ds_read_b128 v[190:193], v151 offset:20480
	ds_read_b128 v[194:197], v151 offset:21504
	ds_read_b128 v[198:201], v151 offset:22528
	ds_read_b128 v[202:205], v151 offset:23552
	global_load_lds_dwordx4 v[182:183], off
	v_lshl_add_u64 v[222:223], s[60:61], 0, v[130:131]
	s_mov_b32 m0, s35
	s_nop 0
	global_load_lds_dwordx4 v[222:223], off
	s_barrier
	s_waitcnt lgkmcnt(0)
	s_setprio 1
	s_waitcnt lgkmcnt(0)
	v_mfma_f32_16x16x32_bf16 v[60:63], v[140:143], v[170:173], v[60:63]
	v_mfma_f32_16x16x32_bf16 v[56:59], v[162:165], v[170:173], v[56:59]
	v_mfma_f32_16x16x32_bf16 v[44:47], v[140:143], v[178:181], v[44:47]
	v_mfma_f32_16x16x32_bf16 v[40:43], v[162:165], v[178:181], v[40:43]
	v_mfma_f32_16x16x32_bf16 v[28:31], v[140:143], v[190:193], v[28:31]
	v_mfma_f32_16x16x32_bf16 v[24:27], v[162:165], v[190:193], v[24:27]
	v_mfma_f32_16x16x32_bf16 v[12:15], v[140:143], v[198:201], v[12:15]
	v_mfma_f32_16x16x32_bf16 v[8:11], v[162:165], v[198:201], v[8:11]
	v_mfma_f32_16x16x32_bf16 v[60:63], v[158:161], v[174:177], v[60:63]
	v_mfma_f32_16x16x32_bf16 v[56:59], v[166:169], v[174:177], v[56:59]
	v_mfma_f32_16x16x32_bf16 v[44:47], v[158:161], v[186:189], v[44:47]
	v_mfma_f32_16x16x32_bf16 v[40:43], v[166:169], v[186:189], v[40:43]
	v_mfma_f32_16x16x32_bf16 v[28:31], v[158:161], v[194:197], v[28:31]
	v_mfma_f32_16x16x32_bf16 v[24:27], v[166:169], v[194:197], v[24:27]
	v_mfma_f32_16x16x32_bf16 v[12:15], v[158:161], v[202:205], v[12:15]
	v_mfma_f32_16x16x32_bf16 v[8:11], v[166:169], v[202:205], v[8:11]
	s_setprio 0
	s_barrier
; #define PG8_STAGE(bufoff, gbase, voff) do { _Pragma("unroll") for (int _i = 0; _i < 2; ++_i) \
;         __builtin_amdgcn_global_load_lds((const unsigned*)((const char*)(gbase) + (voff)[_i]), (LAS unsigned*)(lds + (bufoff) + ldsw + _i * 8192), 16, 0, 0); } while (0)
; #define PG8_LDA(dst, b, h) do { _Pragma("unroll") for (int m = 0; m < 4; ++m) _Pragma("unroll") for (int k = 0; k < 2; ++k) dst[m][k] = *(const LAS bf16x8*)(lds + PG8_SA(b, h) + aoff + m * 2048 + k * 1024); } while (0)
; #define PG8_LDB(dst, b, h) do { _Pragma("unroll") for (int n = 0; n < 2; ++n) _Pragma("unroll") for (int k = 0; k < 2; ++k) dst[n][k] = *(const LAS bf16x8*)(lds + PG8_SB(b, h) + boff + n * 2048 + k * 1024); } while (0)
; #define PG8_MMA(ai, bj, At, Bt) do { __builtin_amdgcn_s_setprio(1); _Pragma("unroll") for (int m = 0; m < 4; ++m) _Pragma("unroll") for (int n = 0; n < 2; ++n) _Pragma("unroll") for (int k = 0; k < 2; ++k) \
;         acc[ai][bj][m][n] = __builtin_amdgcn_mfma_f32_16x16x32_bf16(Bt[n][k], At[m][k], acc[ai][bj][m][n], 0, 0, 0); __builtin_amdgcn_s_setprio(0); } while (0)
; #define PG8_WAIT_V(n) asm volatile("s_waitcnt vmcnt(" #n ")" ::: "memory")
; #define PG8_WAIT_L(n) asm volatile("s_waitcnt lgkmcnt(" #n ")" ::: "memory")
; #define PG8_BAR __builtin_amdgcn_s_barrier()
; #define PG8_SCHED __builtin_amdgcn_sched_barrier(0)
; template <class Epi>
; __device__ __forceinline__ void gemm_phase(LAS unsigned char* lds, const Gemm g, const StaticOrder& S, const Epi& E) {
;     ...
;             PG8_STAGE(PG8_SB(0, 1), b2 + hstepB, voffB);
;             PG8_WAIT_V(6); PG8_BAR; PG8_MMA(1, 1, At, B1); PG8_BAR;
;             PG8_LDB(B0, 1, 0); PG8_SCHED; PG8_LDA(At, 1, 0); PG8_STAGE(PG8_SA(0, 1), a2 + hstepA, voffA);
;             PG8_WAIT_L(8); PG8_BAR; PG8_WAIT_L(0); PG8_MMA(0, 0, At, B0); PG8_BAR; PG8_SCHED;
;             PG8_LDB(B1, 1, 1); PG8_STAGE(PG8_SB(1, 0), b3, voffB);
;             PG8_BAR; PG8_WAIT_L(0); PG8_MMA(0, 1, At, B1); PG8_BAR;
;             PG8_LDA(At, 1, 1); PG8_STAGE(PG8_SA(1, 0), a3, voffA);
	s_add_u32 s78, s58, 0x40000
	s_addc_u32 s79, s59, 0
	s_add_i32 s77, s74, s31
	v_lshl_add_u64 v[140:141], s[78:79], 0, v[128:129]
	s_mov_b32 m0, s77
	s_nop 0
	global_load_lds_dwordx4 v[140:141], off
	v_lshl_add_u64 v[140:141], s[78:79], 0, v[130:131]
	s_add_i32 m0, s77, 0x2000
	s_nop 0
	global_load_lds_dwordx4 v[140:141], off
	s_waitcnt vmcnt(6)
	s_barrier
	s_setprio 1
	v_mfma_f32_16x16x32_bf16 v[52:55], v[206:209], v[170:173], v[52:55]
	v_mfma_f32_16x16x32_bf16 v[48:51], v[214:217], v[170:173], v[48:51]
	v_mfma_f32_16x16x32_bf16 v[36:39], v[206:209], v[178:181], v[36:39]
	v_mfma_f32_16x16x32_bf16 v[32:35], v[214:217], v[178:181], v[32:35]
	v_mfma_f32_16x16x32_bf16 v[20:23], v[206:209], v[190:193], v[20:23]
	v_mfma_f32_16x16x32_bf16 v[16:19], v[214:217], v[190:193], v[16:19]
	v_mfma_f32_16x16x32_bf16 v[4:7], v[206:209], v[198:201], v[4:7]
	v_mfma_f32_16x16x32_bf16 v[0:3], v[214:217], v[198:201], v[0:3]
	v_mfma_f32_16x16x32_bf16 v[52:55], v[210:213], v[174:177], v[52:55]
	v_mfma_f32_16x16x32_bf16 v[48:51], v[218:221], v[174:177], v[48:51]
	v_mfma_f32_16x16x32_bf16 v[36:39], v[210:213], v[186:189], v[36:39]
	v_mfma_f32_16x16x32_bf16 v[32:35], v[218:221], v[186:189], v[32:35]
	v_mfma_f32_16x16x32_bf16 v[20:23], v[210:213], v[194:197], v[20:23]
	v_mfma_f32_16x16x32_bf16 v[16:19], v[218:221], v[194:197], v[16:19]
	v_mfma_f32_16x16x32_bf16 v[4:7], v[210:213], v[202:205], v[4:7]
	v_mfma_f32_16x16x32_bf16 v[0:3], v[218:221], v[202:205], v[0:3]
	s_setprio 0
	s_add_i32 s77, 0, 0x18000
	v_add_u32_e32 v157, s77, v148
	s_barrier
	ds_read_b128 v[140:143], v157
	ds_read_b128 v[158:161], v157 offset:1024
	ds_read_b128 v[162:165], v157 offset:2048
	ds_read_b128 v[166:169], v157 offset:3072
	s_add_u32 s60, s60, 0x40000
	s_addc_u32 s61, s61, 0
	s_mov_b32 m0, s47
	v_lshl_add_u64 v[206:207], s[60:61], 0, v[128:129]
	ds_read_b128 v[170:173], v151 offset:32768
	ds_read_b128 v[174:177], v151 offset:33792
	ds_read_b128 v[178:181], v151 offset:34816
	ds_read_b128 v[186:189], v151 offset:35840
	ds_read_b128 v[190:193], v151 offset:36864
	ds_read_b128 v[194:197], v151 offset:37888
	ds_read_b128 v[198:201], v151 offset:38912
	ds_read_b128 v[202:205], v151 offset:39936
	global_load_lds_dwordx4 v[206:207], off
	v_lshl_add_u64 v[206:207], s[60:61], 0, v[130:131]
	s_mov_b32 m0, s62
	s_nop 0
	global_load_lds_dwordx4 v[206:207], off
	s_waitcnt lgkmcnt(8)
	s_barrier
	s_waitcnt lgkmcnt(0)
	s_setprio 1
	s_waitcnt lgkmcnt(0)
	v_mfma_f32_16x16x32_bf16 v[124:127], v[140:143], v[170:173], v[124:127]
	v_mfma_f32_16x16x32_bf16 v[120:123], v[162:165], v[170:173], v[120:123]
	v_mfma_f32_16x16x32_bf16 v[108:111], v[140:143], v[178:181], v[108:111]
	v_mfma_f32_16x16x32_bf16 v[104:107], v[162:165], v[178:181], v[104:107]
	v_mfma_f32_16x16x32_bf16 v[92:95], v[140:143], v[190:193], v[92:95]
	v_mfma_f32_16x16x32_bf16 v[88:91], v[162:165], v[190:193], v[88:91]
	v_mfma_f32_16x16x32_bf16 v[76:79], v[140:143], v[198:201], v[76:79]
	v_mfma_f32_16x16x32_bf16 v[72:75], v[162:165], v[198:201], v[72:75]
	v_mfma_f32_16x16x32_bf16 v[124:127], v[158:161], v[174:177], v[124:127]
	v_mfma_f32_16x16x32_bf16 v[120:123], v[166:169], v[174:177], v[120:123]
	v_mfma_f32_16x16x32_bf16 v[108:111], v[158:161], v[186:189], v[108:111]
	v_mfma_f32_16x16x32_bf16 v[104:107], v[166:169], v[186:189], v[104:107]
	v_mfma_f32_16x16x32_bf16 v[92:95], v[158:161], v[194:197], v[92:95]
	v_mfma_f32_16x16x32_bf16 v[88:91], v[166:169], v[194:197], v[88:91]
	v_mfma_f32_16x16x32_bf16 v[76:79], v[158:161], v[202:205], v[76:79]
	v_mfma_f32_16x16x32_bf16 v[72:75], v[166:169], v[202:205], v[72:75]
	s_setprio 0
	s_barrier
	s_add_i32 s60, 0, 0x1c000
	s_add_i32 s61, s77, s31
	v_add_u32_e32 v157, s60, v148
	v_lshl_add_u64 v[144:145], v[144:145], 0, s[18:19]
	s_mov_b32 m0, s61
	ds_read_b128 v[206:209], v157
	ds_read_b128 v[210:213], v157 offset:1024
	ds_read_b128 v[214:217], v157 offset:2048
	ds_read_b128 v[218:221], v157 offset:3072
	global_load_lds_dwordx4 v[144:145], off
	v_lshl_add_u64 v[144:145], v[154:155], 0, s[18:19]
	s_add_i32 m0, s61, 0x2000
	s_nop 0
	global_load_lds_dwordx4 v[144:145], off
	s_barrier
	s_waitcnt lgkmcnt(0)
	s_setprio 1
	s_waitcnt lgkmcnt(0)
	v_mfma_f32_16x16x32_bf16 v[116:119], v[206:209], v[170:173], v[116:119]
	v_mfma_f32_16x16x32_bf16 v[112:115], v[214:217], v[170:173], v[112:115]
	v_mfma_f32_16x16x32_bf16 v[100:103], v[206:209], v[178:181], v[100:103]
	v_mfma_f32_16x16x32_bf16 v[96:99], v[214:217], v[178:181], v[96:99]
	v_mfma_f32_16x16x32_bf16 v[84:87], v[206:209], v[190:193], v[84:87]
	v_mfma_f32_16x16x32_bf16 v[80:83], v[214:217], v[190:193], v[80:83]
	v_mfma_f32_16x16x32_bf16 v[68:71], v[206:209], v[198:201], v[68:71]
	v_mfma_f32_16x16x32_bf16 v[64:67], v[214:217], v[198:201], v[64:67]
	v_mfma_f32_16x16x32_bf16 v[116:119], v[210:213], v[174:177], v[116:119]
	v_mfma_f32_16x16x32_bf16 v[112:115], v[218:221], v[174:177], v[112:115]
	v_mfma_f32_16x16x32_bf16 v[100:103], v[210:213], v[186:189], v[100:103]
	v_mfma_f32_16x16x32_bf16 v[96:99], v[218:221], v[186:189], v[96:99]
	v_mfma_f32_16x16x32_bf16 v[84:87], v[210:213], v[194:197], v[84:87]
	v_mfma_f32_16x16x32_bf16 v[80:83], v[218:221], v[194:197], v[80:83]
	v_mfma_f32_16x16x32_bf16 v[68:71], v[210:213], v[202:205], v[68:71]
	v_mfma_f32_16x16x32_bf16 v[64:67], v[218:221], v[202:205], v[64:67]
	s_setprio 0
	s_mov_b32 m0, s66
	v_lshl_add_u64 v[144:145], v[182:183], 0, s[18:19]
	s_barrier
	ds_read_b128 v[170:173], v151 offset:49152
	ds_read_b128 v[174:177], v151 offset:50176
	ds_read_b128 v[178:181], v151 offset:51200
	ds_read_b128 v[186:189], v151 offset:52224
	ds_read_b128 v[190:193], v151 offset:53248
	ds_read_b128 v[194:197], v151 offset:54272
	ds_read_b128 v[198:201], v151 offset:55296
	ds_read_b128 v[202:205], v151 offset:56320
	global_load_lds_dwordx4 v[144:145], off
	v_lshl_add_u64 v[144:145], v[222:223], 0, s[18:19]
	s_mov_b32 m0, s67
	s_nop 0
	global_load_lds_dwordx4 v[144:145], off
	s_barrier
; __device__ __forceinline__ unsigned cvt_pk_bf16(float lo, float hi) { const f32v2_t v = {lo, hi}; const bf16v2_t r = __builtin_convertvector(v, bf16v2_t); return __builtin_bit_cast(unsigned, r); }
; #define PG8_STAGE(bufoff, gbase, voff) do { _Pragma("unroll") for (int _i = 0; _i < 2; ++_i) \
;         __builtin_amdgcn_global_load_lds((const unsigned*)((const char*)(gbase) + (voff)[_i]), (LAS unsigned*)(lds + (bufoff) + ldsw + _i * 8192), 16, 0, 0); } while (0)
; #define PG8_MMA(ai, bj, At, Bt) do { __builtin_amdgcn_s_setprio(1); _Pragma("unroll") for (int m = 0; m < 4; ++m) _Pragma("unroll") for (int n = 0; n < 2; ++n) _Pragma("unroll") for (int k = 0; k < 2; ++k) \
;         acc[ai][bj][m][n] = __builtin_amdgcn_mfma_f32_16x16x32_bf16(Bt[n][k], At[m][k], acc[ai][bj][m][n], 0, 0, 0); __builtin_amdgcn_s_setprio(0); } while (0)
; #define PG8_WAIT_V(n) asm volatile("s_waitcnt vmcnt(" #n ")" ::: "memory")
; #define PG8_BAR __builtin_amdgcn_s_barrier()
; template <class Epi>
; __device__ __forceinline__ void gemm_phase(LAS unsigned char* lds, const Gemm g, const StaticOrder& S, const Epi& E) {
;     ...
;             PG8_BAR; PG8_WAIT_L(0); PG8_MMA(1, 0, At, B0); PG8_BAR; PG8_SCHED;
;             PG8_STAGE(PG8_SB(1, 1), b3 + hstepB, voffB);
;             PG8_WAIT_V(6); PG8_BAR; PG8_MMA(1, 1, At, B1); PG8_BAR;
;     __device__ __forceinline__ void operator()(const f32x4 (&acc)[2][2][4][2], const Unit& u, int wr, int wc, int fr, int fq) const {
;         const int row0 = u.pm * BM + wr * 64 + fr, col0 = u.pn * BM + wc * 32 + 4 * fq;
;         const float* bb = (u.pm < 64) ? base0 : base1 - (size_t)MP * DM;
; #pragma unroll
;         for (int ai = 0; ai < 2; ++ai)
; #pragma unroll
;             for (int m = 0; m < 4; ++m) { const size_t ro = (size_t)(row0 + ai * HALF + m * 16) * DM + col0; float ss = 0.f;
; #pragma unroll
;                 for (int bj = 0; bj < 2; ++bj)
; #pragma unroll
;                     for (int n = 0; n < 2; ++n) {
;                         if constexpr (NORM) {
;                             const f32x4 bv = *(const f32x4*)(bb + ro + bj * HALF + n * 16); const f32x4 v = acc[ai][bj][m][n] + bv;
;                             ss += (v[0] * v[0] + v[1] * v[1]) + (v[2] * v[2] + v[3] * v[3]);
;                             u32x2 w; w.x = cvt_pk_bf16(v[0], v[1]); w.y = cvt_pk_bf16(v[2], v[3]); *(u32x2*)(a3 + ro + bj * HALF + n * 16) = w;
	s_waitcnt lgkmcnt(0)
	s_setprio 1
	s_waitcnt lgkmcnt(0)
	v_mfma_f32_16x16x32_bf16 v[60:63], v[140:143], v[170:173], v[60:63]
	v_mfma_f32_16x16x32_bf16 v[56:59], v[162:165], v[170:173], v[56:59]
	v_mfma_f32_16x16x32_bf16 v[44:47], v[140:143], v[178:181], v[44:47]
	v_mfma_f32_16x16x32_bf16 v[40:43], v[162:165], v[178:181], v[40:43]
	v_mfma_f32_16x16x32_bf16 v[28:31], v[140:143], v[190:193], v[28:31]
	v_mfma_f32_16x16x32_bf16 v[24:27], v[162:165], v[190:193], v[24:27]
	v_mfma_f32_16x16x32_bf16 v[12:15], v[140:143], v[198:201], v[12:15]
	v_mfma_f32_16x16x32_bf16 v[8:11], v[162:165], v[198:201], v[8:11]
	v_mfma_f32_16x16x32_bf16 v[60:63], v[158:161], v[174:177], v[60:63]
	v_mfma_f32_16x16x32_bf16 v[56:59], v[166:169], v[174:177], v[56:59]
	v_mfma_f32_16x16x32_bf16 v[44:47], v[158:161], v[186:189], v[44:47]
	v_mfma_f32_16x16x32_bf16 v[40:43], v[166:169], v[186:189], v[40:43]
	v_mfma_f32_16x16x32_bf16 v[28:31], v[158:161], v[194:197], v[28:31]
	v_mfma_f32_16x16x32_bf16 v[24:27], v[166:169], v[194:197], v[24:27]
	v_mfma_f32_16x16x32_bf16 v[12:15], v[158:161], v[202:205], v[12:15]
	v_mfma_f32_16x16x32_bf16 v[8:11], v[166:169], v[202:205], v[8:11]
	s_setprio 0
	s_barrier
	s_add_u32 s58, s58, 0x40080
	s_addc_u32 s59, s59, 0
	s_add_i32 s60, s60, s31
	v_lshl_add_u64 v[140:141], s[58:59], 0, v[128:129]
	s_mov_b32 m0, s60
	s_nop 0
	global_load_lds_dwordx4 v[140:141], off
	v_lshl_add_u64 v[140:141], s[58:59], 0, v[130:131]
	s_add_i32 m0, s60, 0x2000
	s_nop 0
	global_load_lds_dwordx4 v[140:141], off
	s_waitcnt vmcnt(6)
	s_barrier
	s_setprio 1
	v_mfma_f32_16x16x32_bf16 v[52:55], v[206:209], v[170:173], v[52:55]
	v_mfma_f32_16x16x32_bf16 v[48:51], v[214:217], v[170:173], v[48:51]
	v_mfma_f32_16x16x32_bf16 v[36:39], v[206:209], v[178:181], v[36:39]
	v_mfma_f32_16x16x32_bf16 v[32:35], v[214:217], v[178:181], v[32:35]
	v_mfma_f32_16x16x32_bf16 v[20:23], v[206:209], v[190:193], v[20:23]
	v_mfma_f32_16x16x32_bf16 v[16:19], v[214:217], v[190:193], v[16:19]
	v_mfma_f32_16x16x32_bf16 v[4:7], v[206:209], v[198:201], v[4:7]
	v_mfma_f32_16x16x32_bf16 v[0:3], v[214:217], v[198:201], v[0:3]
	v_mfma_f32_16x16x32_bf16 v[52:55], v[210:213], v[174:177], v[52:55]
	v_mfma_f32_16x16x32_bf16 v[48:51], v[218:221], v[174:177], v[48:51]
	v_mfma_f32_16x16x32_bf16 v[36:39], v[210:213], v[186:189], v[36:39]
	v_mfma_f32_16x16x32_bf16 v[32:35], v[218:221], v[186:189], v[32:35]
	v_mfma_f32_16x16x32_bf16 v[20:23], v[210:213], v[194:197], v[20:23]
	v_mfma_f32_16x16x32_bf16 v[16:19], v[218:221], v[194:197], v[16:19]
	v_mfma_f32_16x16x32_bf16 v[4:7], v[210:213], v[202:205], v[4:7]
	v_mfma_f32_16x16x32_bf16 v[0:3], v[218:221], v[202:205], v[0:3]
	s_setprio 0
	s_add_i32 s76, s76, 2
	s_add_u32 s56, s56, 0x100
	s_addc_u32 s57, s57, 0
	s_add_u32 s43, s43, 0x100
	s_addc_u32 s75, s75, 0
	s_cmp_gt_u32 s76, 13
	s_barrier
	s_cbranch_scc0 .LBB0_752
	v_lshl_add_u32 v144, s42, 8, v147
	v_lshl_or_b32 v142, s46, 8, v149
	v_ashrrev_i32_e32 v145, 31, v144
	s_cmp_lt_i32 s42, 64
	v_ashrrev_i32_e32 v143, 31, v142
	v_lshlrev_b64 v[140:141], 10, v[144:145]
	s_cselect_b32 s43, s53, s72
	s_cselect_b32 s42, s52, s71
	v_lshl_add_u64 v[140:141], v[140:141], 0, v[142:143]
	v_lshl_add_u64 v[182:183], v[144:145], 2, s[12:13]
	v_lshl_add_u64 v[154:155], v[140:141], 2, s[42:43]
	v_lshl_add_u64 v[142:143], v[140:141], 1, s[10:11]
	s_mov_b64 s[76:77], 0x10000
	s_mov_b64 s[78:79], 0x50000
	s_mov_b64 s[80:81], 0x8000
	s_mov_b64 s[82:83], 0x28000
	s_mov_b64 s[56:57], 0x80000
	v_xor_b32_e32 v226, 16, v153
	v_xor_b32_e32 v227, 32, v153
	v_lshlrev_b32_e32 v226, 2, v226
	v_lshlrev_b32_e32 v227, 2, v227
	global_load_dwordx4 v[158:161], v[154:155], off
	global_load_dwordx4 v[162:165], v[154:155], off offset:64
	global_load_dwordx4 v[166:169], v[154:155], off offset:512
	global_load_dwordx4 v[170:173], v[154:155], off offset:576
	v_lshl_add_u64 v[154:155], v[154:155], 0, s[76:77]
	global_load_dwordx4 v[174:177], v[154:155], off
	global_load_dwordx4 v[178:181], v[154:155], off offset:64
	global_load_dwordx4 v[186:189], v[154:155], off offset:512
	global_load_dwordx4 v[190:193], v[154:155], off offset:576
	v_lshl_add_u64 v[154:155], v[154:155], 0, s[76:77]
	global_load_dwordx4 v[194:197], v[154:155], off
	global_load_dwordx4 v[198:201], v[154:155], off offset:64
	global_load_dwordx4 v[202:205], v[154:155], off offset:512
	global_load_dwordx4 v[206:209], v[154:155], off offset:576
	v_lshl_add_u64 v[154:155], v[154:155], 0, s[76:77]
	global_load_dwordx4 v[210:213], v[154:155], off
	global_load_dwordx4 v[214:217], v[154:155], off offset:64
	global_load_dwordx4 v[218:221], v[154:155], off offset:512
	global_load_dwordx4 v[222:225], v[154:155], off offset:576
	v_lshl_add_u64 v[154:155], v[154:155], 0, s[78:79]
	s_waitcnt vmcnt(15)
	v_pk_add_f32 v[158:159], v[124:125], v[158:159]
	v_pk_add_f32 v[160:161], v[126:127], v[160:161]
	v_cvt_pk_bf16_f32 v228, v158, v159
	v_cvt_pk_bf16_f32 v229, v160, v161
	global_store_dwordx2 v[142:143], v[228:229], off
	v_mul_f32_e32 v232, v159, v159
	v_mul_f32_e32 v233, v161, v161
	v_fmac_f32_e32 v232, v158, v158
	v_fmac_f32_e32 v233, v160, v160
	v_add_f32_e32 v238, v232, v233
	global_load_dwordx4 v[158:161], v[154:155], off
	s_waitcnt vmcnt(16)
	v_pk_add_f32 v[162:163], v[120:121], v[162:163]
	v_pk_add_f32 v[164:165], v[122:123], v[164:165]
	v_cvt_pk_bf16_f32 v230, v162, v163
	v_cvt_pk_bf16_f32 v231, v164, v165
	global_store_dwordx2 v[142:143], v[230:231], off offset:32
	v_mul_f32_e32 v232, v163, v163
	v_mul_f32_e32 v233, v165, v165
	v_fmac_f32_e32 v232, v162, v162
	v_fmac_f32_e32 v233, v164, v164
	v_add_f32_e32 v232, v232, v233
	v_add_f32_e32 v238, v238, v232
	global_load_dwordx4 v[162:165], v[154:155], off offset:64
	s_waitcnt vmcnt(17)
; __device__ __forceinline__ unsigned cvt_pk_bf16(float lo, float hi) { const f32v2_t v = {lo, hi}; const bf16v2_t r = __builtin_convertvector(v, bf16v2_t); return __builtin_bit_cast(unsigned, r); }
;     __device__ __forceinline__ void operator()(const f32x4 (&acc)[2][2][4][2], const Unit& u, int wr, int wc, int fr, int fq) const {
;     ...
;             for (int m = 0; m < 4; ++m) { const size_t ro = (size_t)(row0 + ai * HALF + m * 16) * DM + col0; float ss = 0.f;
; #pragma unroll
;                 for (int bj = 0; bj < 2; ++bj)
; #pragma unroll
;                     for (int n = 0; n < 2; ++n) {
;                         if constexpr (NORM) {
;                             const f32x4 bv = *(const f32x4*)(bb + ro + bj * HALF + n * 16); const f32x4 v = acc[ai][bj][m][n] + bv;
;                             ss += (v[0] * v[0] + v[1] * v[1]) + (v[2] * v[2] + v[3] * v[3]);
;                             u32x2 w; w.x = cvt_pk_bf16(v[0], v[1]); w.y = cvt_pk_bf16(v[2], v[3]); *(u32x2*)(a3 + ro + bj * HALF + n * 16) = w;
	v_pk_add_f32 v[166:167], v[116:117], v[166:167]
	v_pk_add_f32 v[168:169], v[118:119], v[168:169]
	v_cvt_pk_bf16_f32 v228, v166, v167
	v_cvt_pk_bf16_f32 v229, v168, v169
	global_store_dwordx2 v[142:143], v[228:229], off offset:256
	v_mul_f32_e32 v232, v167, v167
	v_mul_f32_e32 v233, v169, v169
	v_fmac_f32_e32 v232, v166, v166
	v_fmac_f32_e32 v233, v168, v168
	v_add_f32_e32 v232, v232, v233
	v_add_f32_e32 v238, v238, v232
	global_load_dwordx4 v[166:169], v[154:155], off offset:512
	s_waitcnt vmcnt(18)
	v_pk_add_f32 v[170:171], v[112:113], v[170:171]
	v_pk_add_f32 v[172:173], v[114:115], v[172:173]
	v_cvt_pk_bf16_f32 v230, v170, v171
	v_cvt_pk_bf16_f32 v231, v172, v173
	global_store_dwordx2 v[142:143], v[230:231], off offset:288
	v_mul_f32_e32 v232, v171, v171
	v_mul_f32_e32 v233, v173, v173
	v_fmac_f32_e32 v232, v170, v170
	v_fmac_f32_e32 v233, v172, v172
	v_add_f32_e32 v232, v232, v233
	v_add_f32_e32 v238, v238, v232
	global_load_dwordx4 v[170:173], v[154:155], off offset:576
	v_lshl_add_u64 v[142:143], v[142:143], 0, s[80:81]
	s_waitcnt vmcnt(19)
	v_pk_add_f32 v[174:175], v[108:109], v[174:175]
	v_pk_add_f32 v[176:177], v[110:111], v[176:177]
	v_cvt_pk_bf16_f32 v228, v174, v175
	v_cvt_pk_bf16_f32 v229, v176, v177
	global_store_dwordx2 v[142:143], v[228:229], off
	v_mul_f32_e32 v232, v175, v175
	v_mul_f32_e32 v233, v177, v177
	v_fmac_f32_e32 v232, v174, v174
	v_fmac_f32_e32 v233, v176, v176
	v_add_f32_e32 v239, v232, v233
	v_lshl_add_u64 v[154:155], v[154:155], 0, s[76:77]
	global_load_dwordx4 v[174:177], v[154:155], off
	s_waitcnt vmcnt(20)
	v_pk_add_f32 v[178:179], v[104:105], v[178:179]
	v_pk_add_f32 v[180:181], v[106:107], v[180:181]
	v_cvt_pk_bf16_f32 v230, v178, v179
	v_cvt_pk_bf16_f32 v231, v180, v181
	global_store_dwordx2 v[142:143], v[230:231], off offset:32
	v_mul_f32_e32 v232, v179, v179
	v_mul_f32_e32 v233, v181, v181
	v_fmac_f32_e32 v232, v178, v178
	v_fmac_f32_e32 v233, v180, v180
	v_add_f32_e32 v232, v232, v233
	v_add_f32_e32 v239, v239, v232
	global_load_dwordx4 v[178:181], v[154:155], off offset:64
	s_waitcnt vmcnt(21)
	v_pk_add_f32 v[186:187], v[100:101], v[186:187]
	v_pk_add_f32 v[188:189], v[102:103], v[188:189]
	v_cvt_pk_bf16_f32 v228, v186, v187
	v_cvt_pk_bf16_f32 v229, v188, v189
	global_store_dwordx2 v[142:143], v[228:229], off offset:256
	v_mul_f32_e32 v232, v187, v187
	v_mul_f32_e32 v233, v189, v189
	v_fmac_f32_e32 v232, v186, v186
	v_fmac_f32_e32 v233, v188, v188
	v_add_f32_e32 v232, v232, v233
	v_add_f32_e32 v239, v239, v232
	global_load_dwordx4 v[186:189], v[154:155], off offset:512
	s_waitcnt vmcnt(22)
	v_pk_add_f32 v[190:191], v[96:97], v[190:191]
	v_pk_add_f32 v[192:193], v[98:99], v[192:193]
	v_cvt_pk_bf16_f32 v230, v190, v191
	v_cvt_pk_bf16_f32 v231, v192, v193
	global_store_dwordx2 v[142:143], v[230:231], off offset:288
	v_mul_f32_e32 v232, v191, v191
	v_mul_f32_e32 v233, v193, v193
	v_fmac_f32_e32 v232, v190, v190
	v_fmac_f32_e32 v233, v192, v192
	v_add_f32_e32 v232, v232, v233
	v_add_f32_e32 v239, v239, v232
	global_load_dwordx4 v[190:193], v[154:155], off offset:576
	v_lshl_add_u64 v[142:143], v[142:143], 0, s[80:81]
	s_waitcnt vmcnt(23)
	v_pk_add_f32 v[194:195], v[92:93], v[194:195]
	v_pk_add_f32 v[196:197], v[94:95], v[196:197]
	v_cvt_pk_bf16_f32 v228, v194, v195
	v_cvt_pk_bf16_f32 v229, v196, v197
	global_store_dwordx2 v[142:143], v[228:229], off
	v_mul_f32_e32 v232, v195, v195
	v_mul_f32_e32 v233, v197, v197
	v_fmac_f32_e32 v232, v194, v194
	v_fmac_f32_e32 v233, v196, v196
	v_add_f32_e32 v240, v232, v233
	v_lshl_add_u64 v[154:155], v[154:155], 0, s[76:77]
	global_load_dwordx4 v[194:197], v[154:155], off
	s_waitcnt vmcnt(24)
	v_pk_add_f32 v[198:199], v[88:89], v[198:199]
	v_pk_add_f32 v[200:201], v[90:91], v[200:201]
	v_cvt_pk_bf16_f32 v230, v198, v199
	v_cvt_pk_bf16_f32 v231, v200, v201
	global_store_dwordx2 v[142:143], v[230:231], off offset:32
	v_mul_f32_e32 v232, v199, v199
	v_mul_f32_e32 v233, v201, v201
	v_fmac_f32_e32 v232, v198, v198
	v_fmac_f32_e32 v233, v200, v200
	v_add_f32_e32 v232, v232, v233
	v_add_f32_e32 v240, v240, v232
	global_load_dwordx4 v[198:201], v[154:155], off offset:64
	s_waitcnt vmcnt(25)
	v_pk_add_f32 v[202:203], v[84:85], v[202:203]
	v_pk_add_f32 v[204:205], v[86:87], v[204:205]
	v_cvt_pk_bf16_f32 v228, v202, v203
	v_cvt_pk_bf16_f32 v229, v204, v205
	global_store_dwordx2 v[142:143], v[228:229], off offset:256
	v_mul_f32_e32 v232, v203, v203
	v_mul_f32_e32 v233, v205, v205
	v_fmac_f32_e32 v232, v202, v202
	v_fmac_f32_e32 v233, v204, v204
	v_add_f32_e32 v232, v232, v233
	v_add_f32_e32 v240, v240, v232
	global_load_dwordx4 v[202:205], v[154:155], off offset:512
	s_waitcnt vmcnt(26)
	v_pk_add_f32 v[206:207], v[80:81], v[206:207]
	v_pk_add_f32 v[208:209], v[82:83], v[208:209]
	v_cvt_pk_bf16_f32 v230, v206, v207
	v_cvt_pk_bf16_f32 v231, v208, v209
	global_store_dwordx2 v[142:143], v[230:231], off offset:288
	v_mul_f32_e32 v232, v207, v207
	v_mul_f32_e32 v233, v209, v209
	v_fmac_f32_e32 v232, v206, v206
	v_fmac_f32_e32 v233, v208, v208
	v_add_f32_e32 v232, v232, v233
	v_add_f32_e32 v240, v240, v232
	global_load_dwordx4 v[206:209], v[154:155], off offset:576
	v_lshl_add_u64 v[142:143], v[142:143], 0, s[80:81]
	s_waitcnt vmcnt(27)
	v_pk_add_f32 v[210:211], v[76:77], v[210:211]
	v_pk_add_f32 v[212:213], v[78:79], v[212:213]
	v_cvt_pk_bf16_f32 v228, v210, v211
	v_cvt_pk_bf16_f32 v229, v212, v213
	global_store_dwordx2 v[142:143], v[228:229], off
	v_mul_f32_e32 v232, v211, v211
	v_mul_f32_e32 v233, v213, v213
	v_fmac_f32_e32 v232, v210, v210
	v_fmac_f32_e32 v233, v212, v212
	v_add_f32_e32 v241, v232, v233
	v_lshl_add_u64 v[154:155], v[154:155], 0, s[76:77]
	global_load_dwordx4 v[210:213], v[154:155], off
	s_waitcnt vmcnt(28)
; __device__ __forceinline__ unsigned cvt_pk_bf16(float lo, float hi) { const f32v2_t v = {lo, hi}; const bf16v2_t r = __builtin_convertvector(v, bf16v2_t); return __builtin_bit_cast(unsigned, r); }
;     __device__ __forceinline__ void operator()(const f32x4 (&acc)[2][2][4][2], const Unit& u, int wr, int wc, int fr, int fq) const {
;     ...
;             for (int m = 0; m < 4; ++m) { const size_t ro = (size_t)(row0 + ai * HALF + m * 16) * DM + col0; float ss = 0.f;
; #pragma unroll
;                 for (int bj = 0; bj < 2; ++bj)
; #pragma unroll
;                     for (int n = 0; n < 2; ++n) {
;                         if constexpr (NORM) {
;                             const f32x4 bv = *(const f32x4*)(bb + ro + bj * HALF + n * 16); const f32x4 v = acc[ai][bj][m][n] + bv;
;                             ss += (v[0] * v[0] + v[1] * v[1]) + (v[2] * v[2] + v[3] * v[3]);
;                             u32x2 w; w.x = cvt_pk_bf16(v[0], v[1]); w.y = cvt_pk_bf16(v[2], v[3]); *(u32x2*)(a3 + ro + bj * HALF + n * 16) = w;
	v_pk_add_f32 v[214:215], v[72:73], v[214:215]
	v_pk_add_f32 v[216:217], v[74:75], v[216:217]
	v_cvt_pk_bf16_f32 v230, v214, v215
	v_cvt_pk_bf16_f32 v231, v216, v217
	global_store_dwordx2 v[142:143], v[230:231], off offset:32
	v_mul_f32_e32 v232, v215, v215
	v_mul_f32_e32 v233, v217, v217
	v_fmac_f32_e32 v232, v214, v214
	v_fmac_f32_e32 v233, v216, v216
	v_add_f32_e32 v232, v232, v233
	v_add_f32_e32 v241, v241, v232
	global_load_dwordx4 v[214:217], v[154:155], off offset:64
	s_waitcnt vmcnt(29)
	v_pk_add_f32 v[218:219], v[68:69], v[218:219]
	v_pk_add_f32 v[220:221], v[70:71], v[220:221]
	v_cvt_pk_bf16_f32 v228, v218, v219
	v_cvt_pk_bf16_f32 v229, v220, v221
	global_store_dwordx2 v[142:143], v[228:229], off offset:256
	v_mul_f32_e32 v232, v219, v219
	v_mul_f32_e32 v233, v221, v221
	v_fmac_f32_e32 v232, v218, v218
	v_fmac_f32_e32 v233, v220, v220
	v_add_f32_e32 v232, v232, v233
	v_add_f32_e32 v241, v241, v232
	global_load_dwordx4 v[218:221], v[154:155], off offset:512
	s_waitcnt vmcnt(30)
	v_pk_add_f32 v[222:223], v[64:65], v[222:223]
	v_pk_add_f32 v[224:225], v[66:67], v[224:225]
	v_cvt_pk_bf16_f32 v230, v222, v223
	v_cvt_pk_bf16_f32 v231, v224, v225
	global_store_dwordx2 v[142:143], v[230:231], off offset:288
	v_mul_f32_e32 v232, v223, v223
	v_mul_f32_e32 v233, v225, v225
	v_fmac_f32_e32 v232, v222, v222
	v_fmac_f32_e32 v233, v224, v224
	v_add_f32_e32 v232, v232, v233
	v_add_f32_e32 v241, v241, v232
	global_load_dwordx4 v[222:225], v[154:155], off offset:576
	v_lshl_add_u64 v[142:143], v[142:143], 0, s[82:83]
	s_waitcnt vmcnt(30)
	v_pk_add_f32 v[158:159], v[60:61], v[158:159]
	v_pk_add_f32 v[160:161], v[62:63], v[160:161]
	v_cvt_pk_bf16_f32 v228, v158, v159
	v_cvt_pk_bf16_f32 v229, v160, v161
	global_store_dwordx2 v[142:143], v[228:229], off
	v_mul_f32_e32 v232, v159, v159
	v_mul_f32_e32 v233, v161, v161
	v_fmac_f32_e32 v232, v158, v158
	v_fmac_f32_e32 v233, v160, v160
	v_add_f32_e32 v242, v232, v233
	s_waitcnt vmcnt(29)
	v_pk_add_f32 v[162:163], v[56:57], v[162:163]
	v_pk_add_f32 v[164:165], v[58:59], v[164:165]
	v_cvt_pk_bf16_f32 v230, v162, v163
	v_cvt_pk_bf16_f32 v231, v164, v165
	global_store_dwordx2 v[142:143], v[230:231], off offset:32
	v_mul_f32_e32 v232, v163, v163
	v_mul_f32_e32 v233, v165, v165
	v_fmac_f32_e32 v232, v162, v162
	v_fmac_f32_e32 v233, v164, v164
	v_add_f32_e32 v232, v232, v233
	v_add_f32_e32 v242, v242, v232
	s_waitcnt vmcnt(28)
	v_pk_add_f32 v[166:167], v[52:53], v[166:167]
	v_pk_add_f32 v[168:169], v[54:55], v[168:169]
	v_cvt_pk_bf16_f32 v228, v166, v167
	v_cvt_pk_bf16_f32 v229, v168, v169
	global_store_dwordx2 v[142:143], v[228:229], off offset:256
	v_mul_f32_e32 v232, v167, v167
	v_mul_f32_e32 v233, v169, v169
	v_fmac_f32_e32 v232, v166, v166
	v_fmac_f32_e32 v233, v168, v168
	v_add_f32_e32 v232, v232, v233
	v_add_f32_e32 v242, v242, v232
	s_waitcnt vmcnt(27)
	v_pk_add_f32 v[170:171], v[48:49], v[170:171]
	v_pk_add_f32 v[172:173], v[50:51], v[172:173]
	v_cvt_pk_bf16_f32 v230, v170, v171
	v_cvt_pk_bf16_f32 v231, v172, v173
	global_store_dwordx2 v[142:143], v[230:231], off offset:288
	v_mul_f32_e32 v232, v171, v171
	v_mul_f32_e32 v233, v173, v173
	v_fmac_f32_e32 v232, v170, v170
	v_fmac_f32_e32 v233, v172, v172
	v_add_f32_e32 v232, v232, v233
	v_add_f32_e32 v242, v242, v232
	v_lshl_add_u64 v[142:143], v[142:143], 0, s[80:81]
	s_waitcnt vmcnt(26)
	v_pk_add_f32 v[174:175], v[44:45], v[174:175]
	v_pk_add_f32 v[176:177], v[46:47], v[176:177]
	v_cvt_pk_bf16_f32 v228, v174, v175
	v_cvt_pk_bf16_f32 v229, v176, v177
	global_store_dwordx2 v[142:143], v[228:229], off
	v_mul_f32_e32 v232, v175, v175
	v_mul_f32_e32 v233, v177, v177
	v_fmac_f32_e32 v232, v174, v174
	v_fmac_f32_e32 v233, v176, v176
	v_add_f32_e32 v243, v232, v233
	s_waitcnt vmcnt(25)
	v_pk_add_f32 v[178:179], v[40:41], v[178:179]
	v_pk_add_f32 v[180:181], v[42:43], v[180:181]
	v_cvt_pk_bf16_f32 v230, v178, v179
	v_cvt_pk_bf16_f32 v231, v180, v181
	global_store_dwordx2 v[142:143], v[230:231], off offset:32
	v_mul_f32_e32 v232, v179, v179
	v_mul_f32_e32 v233, v181, v181
	v_fmac_f32_e32 v232, v178, v178
	v_fmac_f32_e32 v233, v180, v180
	v_add_f32_e32 v232, v232, v233
	v_add_f32_e32 v243, v243, v232
	s_waitcnt vmcnt(24)
	v_pk_add_f32 v[186:187], v[36:37], v[186:187]
	v_pk_add_f32 v[188:189], v[38:39], v[188:189]
	v_cvt_pk_bf16_f32 v228, v186, v187
	v_cvt_pk_bf16_f32 v229, v188, v189
	global_store_dwordx2 v[142:143], v[228:229], off offset:256
	v_mul_f32_e32 v232, v187, v187
	v_mul_f32_e32 v233, v189, v189
	v_fmac_f32_e32 v232, v186, v186
	v_fmac_f32_e32 v233, v188, v188
	v_add_f32_e32 v232, v232, v233
	v_add_f32_e32 v243, v243, v232
	s_waitcnt vmcnt(23)
	v_pk_add_f32 v[190:191], v[32:33], v[190:191]
	v_pk_add_f32 v[192:193], v[34:35], v[192:193]
	v_cvt_pk_bf16_f32 v230, v190, v191
	v_cvt_pk_bf16_f32 v231, v192, v193
	global_store_dwordx2 v[142:143], v[230:231], off offset:288
	v_mul_f32_e32 v232, v191, v191
	v_mul_f32_e32 v233, v193, v193
	v_fmac_f32_e32 v232, v190, v190
	v_fmac_f32_e32 v233, v192, v192
	v_add_f32_e32 v232, v232, v233
	v_add_f32_e32 v243, v243, v232
	v_lshl_add_u64 v[142:143], v[142:143], 0, s[80:81]
	s_waitcnt vmcnt(22)
; __device__ __forceinline__ unsigned cvt_pk_bf16(float lo, float hi) { const f32v2_t v = {lo, hi}; const bf16v2_t r = __builtin_convertvector(v, bf16v2_t); return __builtin_bit_cast(unsigned, r); }
; __device__ __forceinline__ float bf2f(short b) { return __uint_as_float(((unsigned)(unsigned short)b) << 16); }
;     __device__ __forceinline__ void operator()(const f32x4 (&acc)[2][2][4][2], const Unit& u, int wr, int wc, int fr, int fq) const {
;     ...
;             for (int m = 0; m < 4; ++m) { const size_t ro = (size_t)(row0 + ai * HALF + m * 16) * DM + col0; float ss = 0.f;
; #pragma unroll
;                 for (int bj = 0; bj < 2; ++bj)
; #pragma unroll
;                     for (int n = 0; n < 2; ++n) {
;                         if constexpr (NORM) {
;                             const f32x4 bv = *(const f32x4*)(bb + ro + bj * HALF + n * 16); const f32x4 v = acc[ai][bj][m][n] + bv;
;                             ss += (v[0] * v[0] + v[1] * v[1]) + (v[2] * v[2] + v[3] * v[3]);
;                             u32x2 w; w.x = cvt_pk_bf16(v[0], v[1]); w.y = cvt_pk_bf16(v[2], v[3]); *(u32x2*)(a3 + ro + bj * HALF + n * 16) = w;
;                         } else {
;                             const bf16x4 hb = *(const bf16x4*)(a3 + ro + bj * HALF + n * 16);
;                             *(f32x4*)(out + ro + bj * HALF + n * 16) = acc[ai][bj][m][n] + (f32x4){bf2f(hb[0]), bf2f(hb[1]), bf2f(hb[2]), bf2f(hb[3])}; } }
;                 if constexpr (NORM) { ss += __shfl_xor(ss, 16); ss += __shfl_xor(ss, 32); if (fq == 0) atomicAdd(rowss + row0 + ai * HALF + m * 16, ss); } }
	v_pk_add_f32 v[194:195], v[28:29], v[194:195]
	v_pk_add_f32 v[196:197], v[30:31], v[196:197]
	v_cvt_pk_bf16_f32 v228, v194, v195
	v_cvt_pk_bf16_f32 v229, v196, v197
	global_store_dwordx2 v[142:143], v[228:229], off
	v_mul_f32_e32 v232, v195, v195
	v_mul_f32_e32 v233, v197, v197
	v_fmac_f32_e32 v232, v194, v194
	v_fmac_f32_e32 v233, v196, v196
	v_add_f32_e32 v244, v232, v233
	s_waitcnt vmcnt(21)
	v_pk_add_f32 v[198:199], v[24:25], v[198:199]
	v_pk_add_f32 v[200:201], v[26:27], v[200:201]
	v_cvt_pk_bf16_f32 v230, v198, v199
	v_cvt_pk_bf16_f32 v231, v200, v201
	global_store_dwordx2 v[142:143], v[230:231], off offset:32
	v_mul_f32_e32 v232, v199, v199
	v_mul_f32_e32 v233, v201, v201
	v_fmac_f32_e32 v232, v198, v198
	v_fmac_f32_e32 v233, v200, v200
	v_add_f32_e32 v232, v232, v233
	v_add_f32_e32 v244, v244, v232
	s_waitcnt vmcnt(20)
	v_pk_add_f32 v[202:203], v[20:21], v[202:203]
	v_pk_add_f32 v[204:205], v[22:23], v[204:205]
	v_cvt_pk_bf16_f32 v228, v202, v203
	v_cvt_pk_bf16_f32 v229, v204, v205
	global_store_dwordx2 v[142:143], v[228:229], off offset:256
	v_mul_f32_e32 v232, v203, v203
	v_mul_f32_e32 v233, v205, v205
	v_fmac_f32_e32 v232, v202, v202
	v_fmac_f32_e32 v233, v204, v204
	v_add_f32_e32 v232, v232, v233
	v_add_f32_e32 v244, v244, v232
	s_waitcnt vmcnt(19)
	v_pk_add_f32 v[206:207], v[16:17], v[206:207]
	v_pk_add_f32 v[208:209], v[18:19], v[208:209]
	v_cvt_pk_bf16_f32 v230, v206, v207
	v_cvt_pk_bf16_f32 v231, v208, v209
	global_store_dwordx2 v[142:143], v[230:231], off offset:288
	v_mul_f32_e32 v232, v207, v207
	v_mul_f32_e32 v233, v209, v209
	v_fmac_f32_e32 v232, v206, v206
	v_fmac_f32_e32 v233, v208, v208
	v_add_f32_e32 v232, v232, v233
	v_add_f32_e32 v244, v244, v232
	v_lshl_add_u64 v[142:143], v[142:143], 0, s[80:81]
	s_waitcnt vmcnt(18)
	v_pk_add_f32 v[210:211], v[12:13], v[210:211]
	v_pk_add_f32 v[212:213], v[14:15], v[212:213]
	v_cvt_pk_bf16_f32 v228, v210, v211
	v_cvt_pk_bf16_f32 v229, v212, v213
	global_store_dwordx2 v[142:143], v[228:229], off
	v_mul_f32_e32 v232, v211, v211
	v_mul_f32_e32 v233, v213, v213
	v_fmac_f32_e32 v232, v210, v210
	v_fmac_f32_e32 v233, v212, v212
	v_add_f32_e32 v245, v232, v233
	s_waitcnt vmcnt(17)
	v_pk_add_f32 v[214:215], v[8:9], v[214:215]
	v_pk_add_f32 v[216:217], v[10:11], v[216:217]
	v_cvt_pk_bf16_f32 v230, v214, v215
	v_cvt_pk_bf16_f32 v231, v216, v217
	global_store_dwordx2 v[142:143], v[230:231], off offset:32
	v_mul_f32_e32 v232, v215, v215
	v_mul_f32_e32 v233, v217, v217
	v_fmac_f32_e32 v232, v214, v214
	v_fmac_f32_e32 v233, v216, v216
	v_add_f32_e32 v232, v232, v233
	v_add_f32_e32 v245, v245, v232
	s_waitcnt vmcnt(16)
	v_pk_add_f32 v[218:219], v[4:5], v[218:219]
	v_pk_add_f32 v[220:221], v[6:7], v[220:221]
	v_cvt_pk_bf16_f32 v228, v218, v219
	v_cvt_pk_bf16_f32 v229, v220, v221
	global_store_dwordx2 v[142:143], v[228:229], off offset:256
	v_mul_f32_e32 v232, v219, v219
	v_mul_f32_e32 v233, v221, v221
	v_fmac_f32_e32 v232, v218, v218
	v_fmac_f32_e32 v233, v220, v220
	v_add_f32_e32 v232, v232, v233
	v_add_f32_e32 v245, v245, v232
	s_waitcnt vmcnt(15)
	v_pk_add_f32 v[222:223], v[0:1], v[222:223]
	v_pk_add_f32 v[224:225], v[2:3], v[224:225]
	v_cvt_pk_bf16_f32 v230, v222, v223
	v_cvt_pk_bf16_f32 v231, v224, v225
	global_store_dwordx2 v[142:143], v[230:231], off offset:288
	v_mul_f32_e32 v232, v223, v223
	v_mul_f32_e32 v233, v225, v225
	v_fmac_f32_e32 v232, v222, v222
	v_fmac_f32_e32 v233, v224, v224
	v_add_f32_e32 v232, v232, v233
	v_add_f32_e32 v245, v245, v232
	ds_bpermute_b32 v158, v226, v238
	ds_bpermute_b32 v159, v226, v239
	ds_bpermute_b32 v160, v226, v240
	ds_bpermute_b32 v161, v226, v241
	ds_bpermute_b32 v162, v226, v242
	ds_bpermute_b32 v163, v226, v243
	ds_bpermute_b32 v164, v226, v244
	ds_bpermute_b32 v165, v226, v245
	s_waitcnt lgkmcnt(0)
	v_add_f32_e32 v238, v238, v158
	v_add_f32_e32 v239, v239, v159
	v_add_f32_e32 v240, v240, v160
	v_add_f32_e32 v241, v241, v161
	v_add_f32_e32 v242, v242, v162
	v_add_f32_e32 v243, v243, v163
	v_add_f32_e32 v244, v244, v164
	v_add_f32_e32 v245, v245, v165
	ds_bpermute_b32 v158, v227, v238
	ds_bpermute_b32 v159, v227, v239
	ds_bpermute_b32 v160, v227, v240
	ds_bpermute_b32 v161, v227, v241
	ds_bpermute_b32 v162, v227, v242
	ds_bpermute_b32 v163, v227, v243
	ds_bpermute_b32 v164, v227, v244
	ds_bpermute_b32 v165, v227, v245
	s_waitcnt lgkmcnt(0)
	v_add_f32_e32 v238, v238, v158
	v_add_f32_e32 v239, v239, v159
	v_add_f32_e32 v240, v240, v160
	v_add_f32_e32 v241, v241, v161
	v_add_f32_e32 v242, v242, v162
	v_add_f32_e32 v243, v243, v163
	v_add_f32_e32 v244, v244, v164
	v_add_f32_e32 v245, v245, v165
	s_and_saveexec_b64 s[0:1], s[4:5]
	global_atomic_add_f32 v[182:183], v238, off
	global_atomic_add_f32 v[182:183], v239, off offset:64
	global_atomic_add_f32 v[182:183], v240, off offset:128
	global_atomic_add_f32 v[182:183], v241, off offset:192
	global_atomic_add_f32 v[182:183], v242, off offset:512
	global_atomic_add_f32 v[182:183], v243, off offset:576
	global_atomic_add_f32 v[182:183], v244, off offset:640
	global_atomic_add_f32 v[182:183], v245, off offset:704
	s_mov_b64 exec, s[0:1]
	s_branch .LBB0_744
